# P3b merge loop: two items per trip, both items' loads in flight before the first compute (de-serialised round trips)
# speedup vs baseline: 1.0025x; 1.0025x over previous
.LBB0_597:
	v_ashrrev_i32_e32 v8, 6, v10
	v_mad_i64_i32 v[12:13], s[0:1], v8, s39, v[6:7]
	global_load_dwordx4 v[12:15], v[12:13], off offset:3072
	v_ashrrev_i32_e32 v9, 31, v8
	v_lshlrev_b64 v[16:17], 5, v[8:9]
	v_lshl_add_u64 v[18:19], v[8:9], 0, s[44:45]
	v_lshl_add_u64 v[20:21], v[8:9], 0, s[46:47]
	v_lshlrev_b64 v[22:23], 10, v[8:9]
	v_lshl_add_u64 v[28:29], v[0:1], 0, v[16:17]
	v_lshlrev_b64 v[16:17], 5, v[18:19]
	v_lshlrev_b64 v[24:25], 5, v[20:21]
	v_lshlrev_b64 v[18:19], 10, v[18:19]
	v_lshlrev_b64 v[20:21], 10, v[20:21]
	v_lshl_add_u64 v[30:31], v[2:3], 0, v[22:23]
	v_lshl_add_u64 v[32:33], v[0:1], 0, v[16:17]
	v_lshl_add_u64 v[34:35], v[0:1], 0, v[24:25]
	v_lshl_add_u64 v[36:37], v[2:3], 0, v[18:19]
	v_lshl_add_u64 v[38:39], v[2:3], 0, v[20:21]
	global_load_dword v11, v[28:29], off
	global_load_dword v44, v[32:33], off
	global_load_dword v45, v[34:35], off
	global_load_dwordx4 v[16:19], v[30:31], off
	global_load_dwordx4 v[20:23], v[36:37], off
	global_load_dwordx4 v[24:27], v[38:39], off
	v_lshlrev_b64 v[8:9], 11, v[8:9]
	v_lshl_add_u64 v[8:9], v[4:5], 0, v[8:9]
	v_add_u32_e32 v102, s38, v10
	v_ashrrev_i32_e32 v100, 6, v102
	v_mad_i64_i32 v[104:105], s[0:1], v100, s39, v[6:7]
	global_load_dwordx4 v[104:107], v[104:105], off offset:3072
	v_ashrrev_i32_e32 v101, 31, v100
	v_lshlrev_b64 v[108:109], 5, v[100:101]
	v_lshl_add_u64 v[110:111], v[100:101], 0, s[44:45]
	v_lshl_add_u64 v[112:113], v[100:101], 0, s[46:47]
	v_lshlrev_b64 v[114:115], 10, v[100:101]
	v_lshl_add_u64 v[120:121], v[0:1], 0, v[108:109]
	v_lshlrev_b64 v[108:109], 5, v[110:111]
	v_lshlrev_b64 v[116:117], 5, v[112:113]
	v_lshlrev_b64 v[110:111], 10, v[110:111]
	v_lshlrev_b64 v[112:113], 10, v[112:113]
	v_lshl_add_u64 v[122:123], v[2:3], 0, v[114:115]
	v_lshl_add_u64 v[124:125], v[0:1], 0, v[108:109]
	v_lshl_add_u64 v[126:127], v[0:1], 0, v[116:117]
	v_lshl_add_u64 v[128:129], v[2:3], 0, v[110:111]
	v_lshl_add_u64 v[130:131], v[2:3], 0, v[112:113]
	global_load_dword v103, v[120:121], off
	global_load_dword v136, v[124:125], off
	global_load_dword v137, v[126:127], off
	global_load_dwordx4 v[108:111], v[122:123], off
	global_load_dwordx4 v[112:115], v[128:129], off
	global_load_dwordx4 v[116:119], v[130:131], off
	v_add_u32_e32 v10, s38, v102
	v_cmp_lt_i32_e32 vcc, s52, v10
	s_or_b64 s[42:43], vcc, s[42:43]
	v_lshlrev_b64 v[100:101], 11, v[100:101]
	v_lshl_add_u64 v[100:101], v[4:5], 0, v[100:101]
	s_waitcnt vmcnt(13)
	v_lshlrev_b32_e32 v47, 16, v13
	v_lshlrev_b32_e32 v49, 16, v12
	v_and_b32_e32 v51, 0xffff0000, v12
	v_and_b32_e32 v50, 0xffff0000, v13
	v_lshlrev_b32_e32 v52, 16, v15
	v_lshlrev_b32_e32 v53, 16, v14
	v_and_b32_e32 v54, 0xffff0000, v15
	v_mul_f32_e32 v12, 0xbfb8aa3b, v49
	v_mul_f32_e32 v13, 0xbfb8aa3b, v51
	v_mul_f32_e32 v15, 0xbfb8aa3b, v47
	v_and_b32_e32 v55, 0xffff0000, v14
	v_mul_f32_e32 v28, 0xbfb8aa3b, v50
	v_mul_f32_e32 v29, 0xbfb8aa3b, v53
	v_mul_f32_e32 v31, 0xbfb8aa3b, v52
	v_exp_f32_e32 v12, v12
	v_exp_f32_e32 v14, v13
	v_exp_f32_e32 v13, v15
	s_waitcnt vmcnt(10)
	v_max3_f32 v46, v11, v44, v45
	v_exp_f32_e32 v15, v28
	v_exp_f32_e32 v28, v29
	v_exp_f32_e32 v29, v31
	v_sub_f32_e32 v11, v11, v46
	v_sub_f32_e32 v44, v44, v46
	v_sub_f32_e32 v46, v45, v46
	v_exp_f32_e32 v45, v11
	v_exp_f32_e32 v44, v44
	v_exp_f32_e32 v11, v46
	v_pk_add_f32 v[12:13], v[12:13], 1.0 op_sel_hi:[1,0]
	v_pk_add_f32 v[14:15], v[14:15], 1.0 op_sel_hi:[1,0]
	v_pk_add_f32 v[28:29], v[28:29], 1.0 op_sel_hi:[1,0]
	v_div_scale_f32 v46, s[0:1], v13, v13, v47
	v_div_scale_f32 v56, s[0:1], v12, v12, v49
	v_div_scale_f32 v58, s[0:1], v15, v15, v50
	v_div_scale_f32 v62, s[0:1], v29, v29, v52
	v_rcp_f32_e32 v70, v46
	v_add_f32_e32 v78, v45, v44
	v_rcp_f32_e32 v71, v56
	v_rcp_f32_e32 v72, v58
	v_rcp_f32_e32 v74, v62
	v_add_f32_e32 v78, v11, v78
	v_div_scale_f32 v79, s[54:55], v78, v78, 1.0
	v_mul_f32_e32 v30, 0xbfb8aa3b, v55
	v_mul_f32_e32 v32, 0xbfb8aa3b, v54
	v_rcp_f32_e32 v81, v79
	v_exp_f32_e32 v30, v30
	v_exp_f32_e32 v31, v32
	v_fma_f32 v82, -v46, v70, 1.0
	v_div_scale_f32 v48, s[10:11], v47, v13, v47
	v_fma_f32 v83, -v56, v71, 1.0
	v_fma_f32 v84, -v58, v72, 1.0
	v_fma_f32 v86, -v62, v74, 1.0
	v_fmac_f32_e32 v70, v82, v70
	v_div_scale_f32 v57, s[12:13], v49, v12, v49
	v_div_scale_f32 v59, s[16:17], v50, v15, v50
	v_div_scale_f32 v60, s[0:1], v14, v14, v51
	v_div_scale_f32 v63, s[8:9], v52, v29, v52
	v_fmac_f32_e32 v71, v83, v71
	v_fmac_f32_e32 v72, v84, v72
	v_fmac_f32_e32 v74, v86, v74
	v_mul_f32_e32 v82, v48, v70
	v_rcp_f32_e32 v73, v60
	v_mul_f32_e32 v83, v57, v71
	v_mul_f32_e32 v84, v59, v72
	v_mul_f32_e32 v86, v63, v74
	v_fma_f32 v90, -v46, v82, v48
	v_fma_f32 v98, -v79, v81, 1.0
	v_pk_add_f32 v[30:31], v[30:31], 1.0 op_sel_hi:[1,0]
	v_div_scale_f32 v64, s[0:1], v28, v28, v53
	v_div_scale_f32 v80, vcc, 1.0, v78, 1.0
	v_fma_f32 v91, -v56, v83, v57
	v_fma_f32 v92, -v58, v84, v59
	v_fma_f32 v94, -v62, v86, v63
	v_fmac_f32_e32 v82, v90, v70
	v_fmac_f32_e32 v81, v98, v81
	v_div_scale_f32 v66, s[0:1], v31, v31, v54
	v_rcp_f32_e32 v75, v64
	v_fmac_f32_e32 v83, v91, v71
	v_fmac_f32_e32 v84, v92, v72
	v_fmac_f32_e32 v86, v94, v74
	v_fma_f32 v48, -v46, v82, v48
	v_mul_f32_e32 v46, v80, v81
	v_div_scale_f32 v68, s[0:1], v30, v30, v55
	v_rcp_f32_e32 v76, v66
	v_fma_f32 v56, -v56, v83, v57
	v_fma_f32 v57, -v58, v84, v59
	v_fma_f32 v59, -v62, v86, v63
	v_fma_f32 v63, -v79, v46, v80
	v_rcp_f32_e32 v77, v68
	v_fma_f32 v85, -v60, v73, 1.0
	v_fmac_f32_e32 v46, v63, v81
	v_div_scale_f32 v61, s[18:19], v51, v14, v51
	v_fmac_f32_e32 v73, v85, v73
	v_fma_f32 v63, -v79, v46, v80
	v_fma_f32 v87, -v64, v75, 1.0
	v_mul_f32_e32 v85, v61, v73
	v_div_fmas_f32 v46, v63, v81, v46
	s_mov_b64 vcc, s[10:11]
	v_div_scale_f32 v65, s[6:7], v53, v28, v53
	v_fma_f32 v88, -v66, v76, 1.0
	v_fmac_f32_e32 v75, v87, v75
	v_fma_f32 v93, -v60, v85, v61
	v_div_fixup_f32 v46, v46, v78, 1.0
	v_div_fmas_f32 v63, v48, v70, v82
	s_mov_b64 vcc, s[12:13]
	s_waitcnt vmcnt(9)
	v_lshlrev_b32_e32 v33, 16, v17
	v_and_b32_e32 v35, 0xffff0000, v17
	v_lshlrev_b32_e32 v36, 16, v16
	s_waitcnt vmcnt(8)
	v_and_b32_e32 v17, 0xffff0000, v21
	v_and_b32_e32 v16, 0xffff0000, v16
	v_div_scale_f32 v67, s[4:5], v54, v31, v54
	v_fma_f32 v89, -v68, v77, 1.0
	v_fmac_f32_e32 v76, v88, v76
	v_mul_f32_e32 v87, v65, v75
	v_fmac_f32_e32 v85, v93, v73
	v_mul_f32_e32 v48, v11, v46
	v_pk_mul_f32 v[44:45], v[44:45], v[46:47] op_sel_hi:[1,0]
	v_div_fmas_f32 v11, v56, v71, v83
	s_mov_b64 vcc, s[16:17]
	v_and_b32_e32 v34, 0xffff0000, v20
	v_div_scale_f32 v69, s[0:1], v55, v30, v55
	v_fmac_f32_e32 v77, v89, v77
	v_mul_f32_e32 v88, v67, v76
	v_fma_f32 v95, -v64, v87, v65
	v_fma_f32 v58, -v60, v85, v61
	v_div_fixup_f32 v12, v11, v12, v49
	v_pk_mul_f32 v[16:17], v[44:45], v[16:17] op_sel:[1,0] op_sel_hi:[0,1]
	v_div_fmas_f32 v11, v57, v72, v84
	s_mov_b64 vcc, s[18:19]
	v_lshlrev_b32_e32 v32, 16, v20
	v_lshlrev_b32_e32 v37, 16, v21
	s_waitcnt vmcnt(7)
	v_lshlrev_b32_e32 v21, 16, v25
	v_lshlrev_b32_e32 v20, 16, v24
	v_and_b32_e32 v25, 0xffff0000, v25
	v_and_b32_e32 v24, 0xffff0000, v24
	v_mul_f32_e32 v89, v69, v77
	v_fma_f32 v96, -v66, v88, v67
	v_fmac_f32_e32 v87, v95, v75
	v_pk_fma_f32 v[16:17], v[44:45], v[34:35], v[16:17]
	v_div_fixup_f32 v15, v11, v15, v50
	v_div_fmas_f32 v11, v58, v73, v85
	s_mov_b64 vcc, s[8:9]
	v_lshlrev_b32_e32 v42, 16, v18
	v_lshlrev_b32_e32 v43, 16, v23
	v_fma_f32 v97, -v68, v89, v69
	v_fmac_f32_e32 v88, v96, v76
	v_fma_f32 v60, -v64, v87, v65
	v_pk_mul_f32 v[36:37], v[44:45], v[36:37] op_sel:[1,0] op_sel_hi:[0,1]
	v_pk_fma_f32 v[16:17], v[48:49], v[24:25], v[16:17] op_sel_hi:[0,1,1]
	v_div_fixup_f32 v14, v11, v14, v51
	v_div_fmas_f32 v11, v59, v74, v86
	s_mov_b64 vcc, s[6:7]
	v_lshlrev_b32_e32 v39, 16, v19
	v_lshlrev_b32_e32 v38, 16, v22
	v_and_b32_e32 v41, 0xffff0000, v19
	v_and_b32_e32 v19, 0xffff0000, v23
	v_and_b32_e32 v18, 0xffff0000, v18
	v_fmac_f32_e32 v89, v97, v77
	v_fma_f32 v61, -v66, v88, v67
	v_pk_mul_f32 v[42:43], v[44:45], v[42:43] op_sel:[1,0] op_sel_hi:[0,1]
	v_pk_fma_f32 v[32:33], v[44:45], v[32:33], v[36:37]
	v_pk_mul_f32 v[14:15], v[16:17], v[14:15]
	v_div_fixup_f32 v17, v11, v29, v52
	v_div_fmas_f32 v11, v60, v75, v87
	s_mov_b64 vcc, s[4:5]
	v_and_b32_e32 v40, 0xffff0000, v22
	v_lshlrev_b32_e32 v23, 16, v27
	v_lshlrev_b32_e32 v22, 16, v26
	v_fma_f32 v62, -v68, v89, v69
	v_div_fixup_f32 v13, v63, v13, v47
	v_pk_mul_f32 v[18:19], v[44:45], v[18:19] op_sel:[1,0] op_sel_hi:[0,1]
	v_pk_fma_f32 v[34:35], v[44:45], v[38:39], v[42:43]
	v_pk_fma_f32 v[20:21], v[48:49], v[20:21], v[32:33] op_sel_hi:[0,1,1]
	v_div_fixup_f32 v16, v11, v28, v53
	v_div_fmas_f32 v11, v61, v76, v88
	s_mov_b64 vcc, s[0:1]
	v_and_b32_e32 v27, 0xffff0000, v27
	v_and_b32_e32 v26, 0xffff0000, v26
	v_pk_fma_f32 v[18:19], v[44:45], v[40:41], v[18:19]
	v_pk_fma_f32 v[22:23], v[48:49], v[22:23], v[34:35] op_sel_hi:[0,1,1]
	v_pk_mul_f32 v[12:13], v[20:21], v[12:13]
	v_bfe_u32 v20, v15, 16, 1
	v_div_fixup_f32 v21, v11, v31, v54
	v_div_fmas_f32 v11, v62, v77, v89
	v_pk_fma_f32 v[18:19], v[48:49], v[26:27], v[18:19] op_sel_hi:[0,1,1]
	v_bfe_u32 v24, v14, 16, 1
	v_pk_mul_f32 v[16:17], v[22:23], v[16:17]
	v_add3_u32 v23, v15, v20, s49
	v_div_fixup_f32 v20, v11, v30, v55
	v_bfe_u32 v25, v12, 16, 1
	v_bfe_u32 v26, v13, 16, 1
	v_add3_u32 v22, v14, v24, s49
	v_bfe_u32 v11, v16, 16, 1
	v_bfe_u32 v24, v17, 16, 1
	v_pk_mul_f32 v[14:15], v[18:19], v[20:21]
	v_add3_u32 v13, v13, v26, s49
	v_add3_u32 v12, v12, v25, s49
	v_add3_u32 v17, v17, v24, s49
	v_add3_u32 v11, v16, v11, s49
	v_bfe_u32 v16, v15, 16, 1
	v_bfe_u32 v18, v14, 16, 1
	v_lshrrev_b32_e32 v12, 16, v12
	v_lshrrev_b32_e32 v13, 16, v13
	v_lshrrev_b32_e32 v11, 16, v11
	v_lshrrev_b32_e32 v17, 16, v17
	v_add3_u32 v14, v14, v18, s49
	v_add3_u32 v15, v15, v16, s49
	v_and_or_b32 v13, v23, s48, v13
	v_and_or_b32 v12, v22, s48, v12
	v_and_or_b32 v15, v15, s48, v17
	v_and_or_b32 v14, v14, s48, v11
	s_waitcnt vmcnt(6)
	v_lshlrev_b32_e32 v139, 16, v105
	v_lshlrev_b32_e32 v141, 16, v104
	v_and_b32_e32 v143, 0xffff0000, v104
	v_and_b32_e32 v142, 0xffff0000, v105
	v_lshlrev_b32_e32 v144, 16, v107
	v_lshlrev_b32_e32 v145, 16, v106
	v_and_b32_e32 v146, 0xffff0000, v107
	v_mul_f32_e32 v104, 0xbfb8aa3b, v141
	v_mul_f32_e32 v105, 0xbfb8aa3b, v143
	v_mul_f32_e32 v107, 0xbfb8aa3b, v139
	v_and_b32_e32 v147, 0xffff0000, v106
	v_mul_f32_e32 v120, 0xbfb8aa3b, v142
	v_mul_f32_e32 v121, 0xbfb8aa3b, v145
	v_mul_f32_e32 v123, 0xbfb8aa3b, v144
	v_exp_f32_e32 v104, v104
	v_exp_f32_e32 v106, v105
	v_exp_f32_e32 v105, v107
	s_waitcnt vmcnt(3)
	v_max3_f32 v138, v103, v136, v137
	v_exp_f32_e32 v107, v120
	v_exp_f32_e32 v120, v121
	v_exp_f32_e32 v121, v123
	v_sub_f32_e32 v103, v103, v138
	v_sub_f32_e32 v136, v136, v138
	v_sub_f32_e32 v138, v137, v138
	v_exp_f32_e32 v137, v103
	v_exp_f32_e32 v136, v136
	v_exp_f32_e32 v103, v138
	v_pk_add_f32 v[104:105], v[104:105], 1.0 op_sel_hi:[1,0]
	v_pk_add_f32 v[106:107], v[106:107], 1.0 op_sel_hi:[1,0]
	v_pk_add_f32 v[120:121], v[120:121], 1.0 op_sel_hi:[1,0]
	v_div_scale_f32 v138, s[0:1], v105, v105, v139
	v_div_scale_f32 v148, s[0:1], v104, v104, v141
	v_div_scale_f32 v150, s[0:1], v107, v107, v142
	v_div_scale_f32 v154, s[0:1], v121, v121, v144
	v_rcp_f32_e32 v162, v138
	v_add_f32_e32 v170, v137, v136
	v_rcp_f32_e32 v163, v148
	v_rcp_f32_e32 v164, v150
	v_rcp_f32_e32 v166, v154
	v_add_f32_e32 v170, v103, v170
	v_div_scale_f32 v171, s[54:55], v170, v170, 1.0
	v_mul_f32_e32 v122, 0xbfb8aa3b, v147
	v_mul_f32_e32 v124, 0xbfb8aa3b, v146
	v_rcp_f32_e32 v173, v171
	v_exp_f32_e32 v122, v122
	v_exp_f32_e32 v123, v124
	v_fma_f32 v174, -v138, v162, 1.0
	v_div_scale_f32 v140, s[10:11], v139, v105, v139
	v_fma_f32 v175, -v148, v163, 1.0
	v_fma_f32 v176, -v150, v164, 1.0
	v_fma_f32 v178, -v154, v166, 1.0
	v_fmac_f32_e32 v162, v174, v162
	v_div_scale_f32 v149, s[12:13], v141, v104, v141
	v_div_scale_f32 v151, s[16:17], v142, v107, v142
	v_div_scale_f32 v152, s[0:1], v106, v106, v143
	v_div_scale_f32 v155, s[8:9], v144, v121, v144
	v_fmac_f32_e32 v163, v175, v163
	v_fmac_f32_e32 v164, v176, v164
	v_fmac_f32_e32 v166, v178, v166
	v_mul_f32_e32 v174, v140, v162
	v_rcp_f32_e32 v165, v152
	v_mul_f32_e32 v175, v149, v163
	v_mul_f32_e32 v176, v151, v164
	v_mul_f32_e32 v178, v155, v166
	v_fma_f32 v182, -v138, v174, v140
	v_fma_f32 v192, -v171, v173, 1.0
	v_pk_add_f32 v[122:123], v[122:123], 1.0 op_sel_hi:[1,0]
	v_div_scale_f32 v156, s[0:1], v120, v120, v145
	v_div_scale_f32 v172, vcc, 1.0, v170, 1.0
	v_fma_f32 v183, -v148, v175, v149
	v_fma_f32 v184, -v150, v176, v151
	v_fma_f32 v188, -v154, v178, v155
	v_fmac_f32_e32 v174, v182, v162
	v_fmac_f32_e32 v173, v192, v173
	v_div_scale_f32 v158, s[0:1], v123, v123, v146
	v_rcp_f32_e32 v167, v156
	v_fmac_f32_e32 v175, v183, v163
	v_fmac_f32_e32 v176, v184, v164
	v_fmac_f32_e32 v178, v188, v166
	v_fma_f32 v140, -v138, v174, v140
	v_mul_f32_e32 v138, v172, v173
	v_div_scale_f32 v160, s[0:1], v122, v122, v147
	v_rcp_f32_e32 v168, v158
	v_fma_f32 v148, -v148, v175, v149
	v_fma_f32 v149, -v150, v176, v151
	v_fma_f32 v151, -v154, v178, v155
	v_fma_f32 v155, -v171, v138, v172
	v_rcp_f32_e32 v169, v160
	v_fma_f32 v177, -v152, v165, 1.0
	v_fmac_f32_e32 v138, v155, v173
	v_div_scale_f32 v153, s[18:19], v143, v106, v143
	v_fmac_f32_e32 v165, v177, v165
	v_fma_f32 v155, -v171, v138, v172
	v_fma_f32 v179, -v156, v167, 1.0
	v_mul_f32_e32 v177, v153, v165
	v_div_fmas_f32 v138, v155, v173, v138
	s_mov_b64 vcc, s[10:11]
	v_div_scale_f32 v157, s[6:7], v145, v120, v145
	v_fma_f32 v180, -v158, v168, 1.0
	v_fmac_f32_e32 v167, v179, v167
	v_fma_f32 v185, -v152, v177, v153
	v_div_fixup_f32 v138, v138, v170, 1.0
	v_div_fmas_f32 v155, v140, v162, v174
	s_mov_b64 vcc, s[12:13]
	s_waitcnt vmcnt(2)
	v_lshlrev_b32_e32 v125, 16, v109
	v_and_b32_e32 v127, 0xffff0000, v109
	v_lshlrev_b32_e32 v128, 16, v108
	s_waitcnt vmcnt(1)
	v_and_b32_e32 v109, 0xffff0000, v113
	v_and_b32_e32 v108, 0xffff0000, v108
	v_div_scale_f32 v159, s[4:5], v146, v123, v146
	v_fma_f32 v181, -v160, v169, 1.0
	v_fmac_f32_e32 v168, v180, v168
	v_mul_f32_e32 v179, v157, v167
	v_fmac_f32_e32 v177, v185, v165
	v_mul_f32_e32 v140, v103, v138
	v_pk_mul_f32 v[136:137], v[136:137], v[138:139] op_sel_hi:[1,0]
	v_div_fmas_f32 v103, v148, v163, v175
	s_mov_b64 vcc, s[16:17]
	v_and_b32_e32 v126, 0xffff0000, v112
	v_div_scale_f32 v161, s[0:1], v147, v122, v147
	v_fmac_f32_e32 v169, v181, v169
	v_mul_f32_e32 v180, v159, v168
	v_fma_f32 v189, -v156, v179, v157
	v_fma_f32 v150, -v152, v177, v153
	v_div_fixup_f32 v104, v103, v104, v141
	v_pk_mul_f32 v[108:109], v[136:137], v[108:109] op_sel:[1,0] op_sel_hi:[0,1]
	v_div_fmas_f32 v103, v149, v164, v176
	s_mov_b64 vcc, s[18:19]
	v_lshlrev_b32_e32 v124, 16, v112
	v_lshlrev_b32_e32 v129, 16, v113
	s_waitcnt vmcnt(0)
	v_lshlrev_b32_e32 v113, 16, v117
	v_lshlrev_b32_e32 v112, 16, v116
	v_and_b32_e32 v117, 0xffff0000, v117
	v_and_b32_e32 v116, 0xffff0000, v116
	v_mul_f32_e32 v181, v161, v169
	v_fma_f32 v190, -v158, v180, v159
	v_fmac_f32_e32 v179, v189, v167
	v_pk_fma_f32 v[108:109], v[136:137], v[126:127], v[108:109]
	v_div_fixup_f32 v107, v103, v107, v142
	v_div_fmas_f32 v103, v150, v165, v177
	s_mov_b64 vcc, s[8:9]
	v_lshlrev_b32_e32 v134, 16, v110
	v_lshlrev_b32_e32 v135, 16, v115
	v_fma_f32 v191, -v160, v181, v161
	v_fmac_f32_e32 v180, v190, v168
	v_fma_f32 v152, -v156, v179, v157
	v_pk_mul_f32 v[128:129], v[136:137], v[128:129] op_sel:[1,0] op_sel_hi:[0,1]
	v_pk_fma_f32 v[108:109], v[140:141], v[116:117], v[108:109] op_sel_hi:[0,1,1]
	v_div_fixup_f32 v106, v103, v106, v143
	v_div_fmas_f32 v103, v151, v166, v178
	s_mov_b64 vcc, s[6:7]
	v_lshlrev_b32_e32 v131, 16, v111
	v_lshlrev_b32_e32 v130, 16, v114
	v_and_b32_e32 v133, 0xffff0000, v111
	v_and_b32_e32 v111, 0xffff0000, v115
	v_and_b32_e32 v110, 0xffff0000, v110
	v_fmac_f32_e32 v181, v191, v169
	v_fma_f32 v153, -v158, v180, v159
	v_pk_mul_f32 v[134:135], v[136:137], v[134:135] op_sel:[1,0] op_sel_hi:[0,1]
	v_pk_fma_f32 v[124:125], v[136:137], v[124:125], v[128:129]
	v_pk_mul_f32 v[106:107], v[108:109], v[106:107]
	v_div_fixup_f32 v109, v103, v121, v144
	v_div_fmas_f32 v103, v152, v167, v179
	s_mov_b64 vcc, s[4:5]
	v_and_b32_e32 v132, 0xffff0000, v114
	v_lshlrev_b32_e32 v115, 16, v119
	v_lshlrev_b32_e32 v114, 16, v118
	v_fma_f32 v154, -v160, v181, v161
	v_div_fixup_f32 v105, v155, v105, v139
	v_pk_mul_f32 v[110:111], v[136:137], v[110:111] op_sel:[1,0] op_sel_hi:[0,1]
	v_pk_fma_f32 v[126:127], v[136:137], v[130:131], v[134:135]
	v_pk_fma_f32 v[112:113], v[140:141], v[112:113], v[124:125] op_sel_hi:[0,1,1]
	v_div_fixup_f32 v108, v103, v120, v145
	v_div_fmas_f32 v103, v153, v168, v180
	s_mov_b64 vcc, s[0:1]
	v_and_b32_e32 v119, 0xffff0000, v119
	v_and_b32_e32 v118, 0xffff0000, v118
	v_pk_fma_f32 v[110:111], v[136:137], v[132:133], v[110:111]
	v_pk_fma_f32 v[114:115], v[140:141], v[114:115], v[126:127] op_sel_hi:[0,1,1]
	v_pk_mul_f32 v[104:105], v[112:113], v[104:105]
	v_bfe_u32 v112, v107, 16, 1
	v_div_fixup_f32 v113, v103, v123, v146
	v_div_fmas_f32 v103, v154, v169, v181
	v_pk_fma_f32 v[110:111], v[140:141], v[118:119], v[110:111] op_sel_hi:[0,1,1]
	v_bfe_u32 v116, v106, 16, 1
	v_pk_mul_f32 v[108:109], v[114:115], v[108:109]
	v_add3_u32 v115, v107, v112, s49
	v_div_fixup_f32 v112, v103, v122, v147
	v_bfe_u32 v117, v104, 16, 1
	v_bfe_u32 v118, v105, 16, 1
	v_add3_u32 v114, v106, v116, s49
	v_bfe_u32 v103, v108, 16, 1
	v_bfe_u32 v116, v109, 16, 1
	v_pk_mul_f32 v[106:107], v[110:111], v[112:113]
	v_add3_u32 v105, v105, v118, s49
	v_add3_u32 v104, v104, v117, s49
	v_add3_u32 v109, v109, v116, s49
	v_add3_u32 v103, v108, v103, s49
	v_bfe_u32 v108, v107, 16, 1
	v_bfe_u32 v110, v106, 16, 1
	v_lshrrev_b32_e32 v104, 16, v104
	v_lshrrev_b32_e32 v105, 16, v105
	v_lshrrev_b32_e32 v103, 16, v103
	v_lshrrev_b32_e32 v109, 16, v109
	v_add3_u32 v106, v106, v110, s49
	v_add3_u32 v107, v107, v108, s49
	v_and_or_b32 v105, v115, s48, v105
	v_and_or_b32 v104, v114, s48, v104
	v_and_or_b32 v107, v107, s48, v109
	v_and_or_b32 v106, v106, s48, v103
	global_store_dwordx4 v[8:9], v[12:15], off
	global_store_dwordx4 v[100:101], v[104:107], off
	s_andn2_b64 exec, exec, s[42:43]
	s_cbranch_execnz .LBB0_597
